# v13 + SCAN phase as a 2-chunk-deep software pipeline (next chunk's loads in flight while the current chunk is stored/updated)
# baseline (speedup 1.0000x reference)
.LBB0_579:
	v_readlane_b32 s0, v254, 8
	v_readlane_b32 s1, v254, 9
	v_and_b32_e32 v6, 0xffff, v51
	v_lshlrev_b32_e32 v6, 2, v6
	v_lshl_or_b32 v6, v2, 23, v6
	v_add_u32_e32 v7, 0x1000000, v6
	v_add_u32_e32 v8, 0x2000000, v6
	v_add_u32_e32 v9, 0x3000000, v6
	s_nop 1
	s_mov_b64 s[4:5], s[0:1]
	global_load_dword v60, v6, s[0:1]
	global_load_dword v64, v36, s[12:13] offset:0
	global_load_dword v61, v7, s[0:1]
	global_load_dword v65, v34, s[12:13] offset:0
	global_load_dword v62, v8, s[0:1]
	global_load_dword v66, v32, s[12:13] offset:0
	global_load_dword v63, v9, s[0:1]
	global_load_dword v67, v30, s[12:13] offset:0
	s_add_u32 s0, s0, 0x40000
	s_addc_u32 s1, s1, 0
	global_load_dword v68, v6, s[0:1]
	global_load_dword v72, v36, s[12:13] offset:64
	global_load_dword v69, v7, s[0:1]
	global_load_dword v73, v34, s[12:13] offset:64
	global_load_dword v70, v8, s[0:1]
	global_load_dword v74, v32, s[12:13] offset:64
	global_load_dword v71, v9, s[0:1]
	global_load_dword v75, v30, s[12:13] offset:64
	s_add_u32 s0, s0, 0x40000
	s_addc_u32 s1, s1, 0
	s_waitcnt vmcnt(8)
	v_cvt_pk_bf16_f32 v52, v48, v49
	v_cvt_pk_bf16_f32 v53, v44, v45
	v_cvt_pk_bf16_f32 v54, v46, v47
	v_cvt_pk_bf16_f32 v55, v40, v41
	global_store_dword v6, v52, s[4:5]
	global_store_dword v7, v53, s[4:5]
	global_store_dword v8, v54, s[4:5]
	global_store_dword v9, v55, s[4:5]
	v_lshlrev_b32_e32 v56, 16, v60
	v_and_b32_e32 v57, 0xffff0000, v60
	v_lshlrev_b32_e32 v58, 16, v61
	v_and_b32_e32 v59, 0xffff0000, v61
	v_lshlrev_b32_e32 v110, 16, v62
	v_and_b32_e32 v111, 0xffff0000, v62
	v_lshlrev_b32_e32 v112, 16, v63
	v_and_b32_e32 v113, 0xffff0000, v63
	v_pk_fma_f32 v[48:49], v[48:49], v[64:65], v[56:57] op_sel_hi:[1,0,1]
	v_pk_fma_f32 v[44:45], v[44:45], v[64:65], v[58:59] op_sel:[0,1,0]
	v_pk_fma_f32 v[46:47], v[46:47], v[66:67], v[110:111] op_sel_hi:[1,0,1]
	v_pk_fma_f32 v[40:41], v[40:41], v[66:67], v[112:113] op_sel:[0,1,0]
	s_add_u32 s4, s4, 0x40000
	s_addc_u32 s5, s5, 0
	global_load_dword v60, v6, s[0:1]
	global_load_dword v64, v36, s[12:13] offset:128
	global_load_dword v61, v7, s[0:1]
	global_load_dword v65, v34, s[12:13] offset:128
	global_load_dword v62, v8, s[0:1]
	global_load_dword v66, v32, s[12:13] offset:128
	global_load_dword v63, v9, s[0:1]
	global_load_dword v67, v30, s[12:13] offset:128
	s_add_u32 s0, s0, 0x40000
	s_addc_u32 s1, s1, 0
	s_waitcnt vmcnt(12)
	v_cvt_pk_bf16_f32 v52, v48, v49
	v_cvt_pk_bf16_f32 v53, v44, v45
	v_cvt_pk_bf16_f32 v54, v46, v47
	v_cvt_pk_bf16_f32 v55, v40, v41
	global_store_dword v6, v52, s[4:5]
	global_store_dword v7, v53, s[4:5]
	global_store_dword v8, v54, s[4:5]
	global_store_dword v9, v55, s[4:5]
	v_lshlrev_b32_e32 v56, 16, v68
	v_and_b32_e32 v57, 0xffff0000, v68
	v_lshlrev_b32_e32 v58, 16, v69
	v_and_b32_e32 v59, 0xffff0000, v69
	v_lshlrev_b32_e32 v110, 16, v70
	v_and_b32_e32 v111, 0xffff0000, v70
	v_lshlrev_b32_e32 v112, 16, v71
	v_and_b32_e32 v113, 0xffff0000, v71
	v_pk_fma_f32 v[48:49], v[48:49], v[72:73], v[56:57] op_sel_hi:[1,0,1]
	v_pk_fma_f32 v[44:45], v[44:45], v[72:73], v[58:59] op_sel:[0,1,0]
	v_pk_fma_f32 v[46:47], v[46:47], v[74:75], v[110:111] op_sel_hi:[1,0,1]
	v_pk_fma_f32 v[40:41], v[40:41], v[74:75], v[112:113] op_sel:[0,1,0]
	s_add_u32 s4, s4, 0x40000
	s_addc_u32 s5, s5, 0
	global_load_dword v68, v6, s[0:1]
	global_load_dword v72, v36, s[12:13] offset:192
	global_load_dword v69, v7, s[0:1]
	global_load_dword v73, v34, s[12:13] offset:192
	global_load_dword v70, v8, s[0:1]
	global_load_dword v74, v32, s[12:13] offset:192
	global_load_dword v71, v9, s[0:1]
	global_load_dword v75, v30, s[12:13] offset:192
	s_add_u32 s0, s0, 0x40000
	s_addc_u32 s1, s1, 0
	s_waitcnt vmcnt(12)
	v_cvt_pk_bf16_f32 v52, v48, v49
	v_cvt_pk_bf16_f32 v53, v44, v45
	v_cvt_pk_bf16_f32 v54, v46, v47
	v_cvt_pk_bf16_f32 v55, v40, v41
	global_store_dword v6, v52, s[4:5]
	global_store_dword v7, v53, s[4:5]
	global_store_dword v8, v54, s[4:5]
	global_store_dword v9, v55, s[4:5]
	v_lshlrev_b32_e32 v56, 16, v60
	v_and_b32_e32 v57, 0xffff0000, v60
	v_lshlrev_b32_e32 v58, 16, v61
	v_and_b32_e32 v59, 0xffff0000, v61
	v_lshlrev_b32_e32 v110, 16, v62
	v_and_b32_e32 v111, 0xffff0000, v62
	v_lshlrev_b32_e32 v112, 16, v63
	v_and_b32_e32 v113, 0xffff0000, v63
	v_pk_fma_f32 v[48:49], v[48:49], v[64:65], v[56:57] op_sel_hi:[1,0,1]
	v_pk_fma_f32 v[44:45], v[44:45], v[64:65], v[58:59] op_sel:[0,1,0]
	v_pk_fma_f32 v[46:47], v[46:47], v[66:67], v[110:111] op_sel_hi:[1,0,1]
	v_pk_fma_f32 v[40:41], v[40:41], v[66:67], v[112:113] op_sel:[0,1,0]
	s_add_u32 s4, s4, 0x40000
	s_addc_u32 s5, s5, 0
	global_load_dword v60, v6, s[0:1]
	global_load_dword v64, v36, s[12:13] offset:256
	global_load_dword v61, v7, s[0:1]
	global_load_dword v65, v34, s[12:13] offset:256
	global_load_dword v62, v8, s[0:1]
	global_load_dword v66, v32, s[12:13] offset:256
	global_load_dword v63, v9, s[0:1]
	global_load_dword v67, v30, s[12:13] offset:256
	s_add_u32 s0, s0, 0x40000
	s_addc_u32 s1, s1, 0
	s_waitcnt vmcnt(12)
	v_cvt_pk_bf16_f32 v52, v48, v49
	v_cvt_pk_bf16_f32 v53, v44, v45
	v_cvt_pk_bf16_f32 v54, v46, v47
	v_cvt_pk_bf16_f32 v55, v40, v41
	global_store_dword v6, v52, s[4:5]
	global_store_dword v7, v53, s[4:5]
	global_store_dword v8, v54, s[4:5]
	global_store_dword v9, v55, s[4:5]
	v_lshlrev_b32_e32 v56, 16, v68
	v_and_b32_e32 v57, 0xffff0000, v68
	v_lshlrev_b32_e32 v58, 16, v69
	v_and_b32_e32 v59, 0xffff0000, v69
	v_lshlrev_b32_e32 v110, 16, v70
	v_and_b32_e32 v111, 0xffff0000, v70
	v_lshlrev_b32_e32 v112, 16, v71
	v_and_b32_e32 v113, 0xffff0000, v71
	v_pk_fma_f32 v[48:49], v[48:49], v[72:73], v[56:57] op_sel_hi:[1,0,1]
	v_pk_fma_f32 v[44:45], v[44:45], v[72:73], v[58:59] op_sel:[0,1,0]
	v_pk_fma_f32 v[46:47], v[46:47], v[74:75], v[110:111] op_sel_hi:[1,0,1]
	v_pk_fma_f32 v[40:41], v[40:41], v[74:75], v[112:113] op_sel:[0,1,0]
	s_add_u32 s4, s4, 0x40000
	s_addc_u32 s5, s5, 0
	global_load_dword v68, v6, s[0:1]
	global_load_dword v72, v36, s[12:13] offset:320
	global_load_dword v69, v7, s[0:1]
	global_load_dword v73, v34, s[12:13] offset:320
	global_load_dword v70, v8, s[0:1]
	global_load_dword v74, v32, s[12:13] offset:320
	global_load_dword v71, v9, s[0:1]
	global_load_dword v75, v30, s[12:13] offset:320
	s_add_u32 s0, s0, 0x40000
	s_addc_u32 s1, s1, 0
	s_waitcnt vmcnt(12)
	v_cvt_pk_bf16_f32 v52, v48, v49
	v_cvt_pk_bf16_f32 v53, v44, v45
	v_cvt_pk_bf16_f32 v54, v46, v47
	v_cvt_pk_bf16_f32 v55, v40, v41
	global_store_dword v6, v52, s[4:5]
	global_store_dword v7, v53, s[4:5]
	global_store_dword v8, v54, s[4:5]
	global_store_dword v9, v55, s[4:5]
	v_lshlrev_b32_e32 v56, 16, v60
	v_and_b32_e32 v57, 0xffff0000, v60
	v_lshlrev_b32_e32 v58, 16, v61
	v_and_b32_e32 v59, 0xffff0000, v61
	v_lshlrev_b32_e32 v110, 16, v62
	v_and_b32_e32 v111, 0xffff0000, v62
	v_lshlrev_b32_e32 v112, 16, v63
	v_and_b32_e32 v113, 0xffff0000, v63
	v_pk_fma_f32 v[48:49], v[48:49], v[64:65], v[56:57] op_sel_hi:[1,0,1]
	v_pk_fma_f32 v[44:45], v[44:45], v[64:65], v[58:59] op_sel:[0,1,0]
	v_pk_fma_f32 v[46:47], v[46:47], v[66:67], v[110:111] op_sel_hi:[1,0,1]
	v_pk_fma_f32 v[40:41], v[40:41], v[66:67], v[112:113] op_sel:[0,1,0]
	s_add_u32 s4, s4, 0x40000
	s_addc_u32 s5, s5, 0
	global_load_dword v60, v6, s[0:1]
	global_load_dword v64, v36, s[12:13] offset:384
	global_load_dword v61, v7, s[0:1]
	global_load_dword v65, v34, s[12:13] offset:384
	global_load_dword v62, v8, s[0:1]
	global_load_dword v66, v32, s[12:13] offset:384
	global_load_dword v63, v9, s[0:1]
	global_load_dword v67, v30, s[12:13] offset:384
	s_add_u32 s0, s0, 0x40000
	s_addc_u32 s1, s1, 0
	s_waitcnt vmcnt(12)
	v_cvt_pk_bf16_f32 v52, v48, v49
	v_cvt_pk_bf16_f32 v53, v44, v45
	v_cvt_pk_bf16_f32 v54, v46, v47
	v_cvt_pk_bf16_f32 v55, v40, v41
	global_store_dword v6, v52, s[4:5]
	global_store_dword v7, v53, s[4:5]
	global_store_dword v8, v54, s[4:5]
	global_store_dword v9, v55, s[4:5]
	v_lshlrev_b32_e32 v56, 16, v68
	v_and_b32_e32 v57, 0xffff0000, v68
	v_lshlrev_b32_e32 v58, 16, v69
	v_and_b32_e32 v59, 0xffff0000, v69
	v_lshlrev_b32_e32 v110, 16, v70
	v_and_b32_e32 v111, 0xffff0000, v70
	v_lshlrev_b32_e32 v112, 16, v71
	v_and_b32_e32 v113, 0xffff0000, v71
	v_pk_fma_f32 v[48:49], v[48:49], v[72:73], v[56:57] op_sel_hi:[1,0,1]
	v_pk_fma_f32 v[44:45], v[44:45], v[72:73], v[58:59] op_sel:[0,1,0]
	v_pk_fma_f32 v[46:47], v[46:47], v[74:75], v[110:111] op_sel_hi:[1,0,1]
	v_pk_fma_f32 v[40:41], v[40:41], v[74:75], v[112:113] op_sel:[0,1,0]
	s_add_u32 s4, s4, 0x40000
	s_addc_u32 s5, s5, 0
	global_load_dword v68, v6, s[0:1]
	global_load_dword v72, v36, s[12:13] offset:448
	global_load_dword v69, v7, s[0:1]
	global_load_dword v73, v34, s[12:13] offset:448
	global_load_dword v70, v8, s[0:1]
	global_load_dword v74, v32, s[12:13] offset:448
	global_load_dword v71, v9, s[0:1]
	global_load_dword v75, v30, s[12:13] offset:448
	s_add_u32 s0, s0, 0x40000
	s_addc_u32 s1, s1, 0
	s_waitcnt vmcnt(12)
	v_cvt_pk_bf16_f32 v52, v48, v49
	v_cvt_pk_bf16_f32 v53, v44, v45
	v_cvt_pk_bf16_f32 v54, v46, v47
	v_cvt_pk_bf16_f32 v55, v40, v41
	global_store_dword v6, v52, s[4:5]
	global_store_dword v7, v53, s[4:5]
	global_store_dword v8, v54, s[4:5]
	global_store_dword v9, v55, s[4:5]
	v_lshlrev_b32_e32 v56, 16, v60
	v_and_b32_e32 v57, 0xffff0000, v60
	v_lshlrev_b32_e32 v58, 16, v61
	v_and_b32_e32 v59, 0xffff0000, v61
	v_lshlrev_b32_e32 v110, 16, v62
	v_and_b32_e32 v111, 0xffff0000, v62
	v_lshlrev_b32_e32 v112, 16, v63
	v_and_b32_e32 v113, 0xffff0000, v63
	v_pk_fma_f32 v[48:49], v[48:49], v[64:65], v[56:57] op_sel_hi:[1,0,1]
	v_pk_fma_f32 v[44:45], v[44:45], v[64:65], v[58:59] op_sel:[0,1,0]
	v_pk_fma_f32 v[46:47], v[46:47], v[66:67], v[110:111] op_sel_hi:[1,0,1]
	v_pk_fma_f32 v[40:41], v[40:41], v[66:67], v[112:113] op_sel:[0,1,0]
	s_add_u32 s4, s4, 0x40000
	s_addc_u32 s5, s5, 0
	global_load_dword v60, v6, s[0:1]
	global_load_dword v64, v36, s[12:13] offset:512
	global_load_dword v61, v7, s[0:1]
	global_load_dword v65, v34, s[12:13] offset:512
	global_load_dword v62, v8, s[0:1]
	global_load_dword v66, v32, s[12:13] offset:512
	global_load_dword v63, v9, s[0:1]
	global_load_dword v67, v30, s[12:13] offset:512
	s_add_u32 s0, s0, 0x40000
	s_addc_u32 s1, s1, 0
	s_waitcnt vmcnt(12)
	v_cvt_pk_bf16_f32 v52, v48, v49
	v_cvt_pk_bf16_f32 v53, v44, v45
	v_cvt_pk_bf16_f32 v54, v46, v47
	v_cvt_pk_bf16_f32 v55, v40, v41
	global_store_dword v6, v52, s[4:5]
	global_store_dword v7, v53, s[4:5]
	global_store_dword v8, v54, s[4:5]
	global_store_dword v9, v55, s[4:5]
	v_lshlrev_b32_e32 v56, 16, v68
	v_and_b32_e32 v57, 0xffff0000, v68
	v_lshlrev_b32_e32 v58, 16, v69
	v_and_b32_e32 v59, 0xffff0000, v69
	v_lshlrev_b32_e32 v110, 16, v70
	v_and_b32_e32 v111, 0xffff0000, v70
	v_lshlrev_b32_e32 v112, 16, v71
	v_and_b32_e32 v113, 0xffff0000, v71
	v_pk_fma_f32 v[48:49], v[48:49], v[72:73], v[56:57] op_sel_hi:[1,0,1]
	v_pk_fma_f32 v[44:45], v[44:45], v[72:73], v[58:59] op_sel:[0,1,0]
	v_pk_fma_f32 v[46:47], v[46:47], v[74:75], v[110:111] op_sel_hi:[1,0,1]
	v_pk_fma_f32 v[40:41], v[40:41], v[74:75], v[112:113] op_sel:[0,1,0]
	s_add_u32 s4, s4, 0x40000
	s_addc_u32 s5, s5, 0
	global_load_dword v68, v6, s[0:1]
	global_load_dword v72, v36, s[12:13] offset:576
	global_load_dword v69, v7, s[0:1]
	global_load_dword v73, v34, s[12:13] offset:576
	global_load_dword v70, v8, s[0:1]
	global_load_dword v74, v32, s[12:13] offset:576
	global_load_dword v71, v9, s[0:1]
	global_load_dword v75, v30, s[12:13] offset:576
	s_add_u32 s0, s0, 0x40000
	s_addc_u32 s1, s1, 0
	s_waitcnt vmcnt(12)
	v_cvt_pk_bf16_f32 v52, v48, v49
	v_cvt_pk_bf16_f32 v53, v44, v45
	v_cvt_pk_bf16_f32 v54, v46, v47
	v_cvt_pk_bf16_f32 v55, v40, v41
	global_store_dword v6, v52, s[4:5]
	global_store_dword v7, v53, s[4:5]
	global_store_dword v8, v54, s[4:5]
	global_store_dword v9, v55, s[4:5]
	v_lshlrev_b32_e32 v56, 16, v60
	v_and_b32_e32 v57, 0xffff0000, v60
	v_lshlrev_b32_e32 v58, 16, v61
	v_and_b32_e32 v59, 0xffff0000, v61
	v_lshlrev_b32_e32 v110, 16, v62
	v_and_b32_e32 v111, 0xffff0000, v62
	v_lshlrev_b32_e32 v112, 16, v63
	v_and_b32_e32 v113, 0xffff0000, v63
	v_pk_fma_f32 v[48:49], v[48:49], v[64:65], v[56:57] op_sel_hi:[1,0,1]
	v_pk_fma_f32 v[44:45], v[44:45], v[64:65], v[58:59] op_sel:[0,1,0]
	v_pk_fma_f32 v[46:47], v[46:47], v[66:67], v[110:111] op_sel_hi:[1,0,1]
	v_pk_fma_f32 v[40:41], v[40:41], v[66:67], v[112:113] op_sel:[0,1,0]
	s_add_u32 s4, s4, 0x40000
	s_addc_u32 s5, s5, 0
	global_load_dword v60, v6, s[0:1]
	global_load_dword v64, v36, s[12:13] offset:640
	global_load_dword v61, v7, s[0:1]
	global_load_dword v65, v34, s[12:13] offset:640
	global_load_dword v62, v8, s[0:1]
	global_load_dword v66, v32, s[12:13] offset:640
	global_load_dword v63, v9, s[0:1]
	global_load_dword v67, v30, s[12:13] offset:640
	s_add_u32 s0, s0, 0x40000
	s_addc_u32 s1, s1, 0
	s_waitcnt vmcnt(12)
	v_cvt_pk_bf16_f32 v52, v48, v49
	v_cvt_pk_bf16_f32 v53, v44, v45
	v_cvt_pk_bf16_f32 v54, v46, v47
	v_cvt_pk_bf16_f32 v55, v40, v41
	global_store_dword v6, v52, s[4:5]
	global_store_dword v7, v53, s[4:5]
	global_store_dword v8, v54, s[4:5]
	global_store_dword v9, v55, s[4:5]
	v_lshlrev_b32_e32 v56, 16, v68
	v_and_b32_e32 v57, 0xffff0000, v68
	v_lshlrev_b32_e32 v58, 16, v69
	v_and_b32_e32 v59, 0xffff0000, v69
	v_lshlrev_b32_e32 v110, 16, v70
	v_and_b32_e32 v111, 0xffff0000, v70
	v_lshlrev_b32_e32 v112, 16, v71
	v_and_b32_e32 v113, 0xffff0000, v71
	v_pk_fma_f32 v[48:49], v[48:49], v[72:73], v[56:57] op_sel_hi:[1,0,1]
	v_pk_fma_f32 v[44:45], v[44:45], v[72:73], v[58:59] op_sel:[0,1,0]
	v_pk_fma_f32 v[46:47], v[46:47], v[74:75], v[110:111] op_sel_hi:[1,0,1]
	v_pk_fma_f32 v[40:41], v[40:41], v[74:75], v[112:113] op_sel:[0,1,0]
	s_add_u32 s4, s4, 0x40000
	s_addc_u32 s5, s5, 0
	global_load_dword v68, v6, s[0:1]
	global_load_dword v72, v36, s[12:13] offset:704
	global_load_dword v69, v7, s[0:1]
	global_load_dword v73, v34, s[12:13] offset:704
	global_load_dword v70, v8, s[0:1]
	global_load_dword v74, v32, s[12:13] offset:704
	global_load_dword v71, v9, s[0:1]
	global_load_dword v75, v30, s[12:13] offset:704
	s_add_u32 s0, s0, 0x40000
	s_addc_u32 s1, s1, 0
	s_waitcnt vmcnt(12)
	v_cvt_pk_bf16_f32 v52, v48, v49
	v_cvt_pk_bf16_f32 v53, v44, v45
	v_cvt_pk_bf16_f32 v54, v46, v47
	v_cvt_pk_bf16_f32 v55, v40, v41
	global_store_dword v6, v52, s[4:5]
	global_store_dword v7, v53, s[4:5]
	global_store_dword v8, v54, s[4:5]
	global_store_dword v9, v55, s[4:5]
	v_lshlrev_b32_e32 v56, 16, v60
	v_and_b32_e32 v57, 0xffff0000, v60
	v_lshlrev_b32_e32 v58, 16, v61
	v_and_b32_e32 v59, 0xffff0000, v61
	v_lshlrev_b32_e32 v110, 16, v62
	v_and_b32_e32 v111, 0xffff0000, v62
	v_lshlrev_b32_e32 v112, 16, v63
	v_and_b32_e32 v113, 0xffff0000, v63
	v_pk_fma_f32 v[48:49], v[48:49], v[64:65], v[56:57] op_sel_hi:[1,0,1]
	v_pk_fma_f32 v[44:45], v[44:45], v[64:65], v[58:59] op_sel:[0,1,0]
	v_pk_fma_f32 v[46:47], v[46:47], v[66:67], v[110:111] op_sel_hi:[1,0,1]
	v_pk_fma_f32 v[40:41], v[40:41], v[66:67], v[112:113] op_sel:[0,1,0]
	s_add_u32 s4, s4, 0x40000
	s_addc_u32 s5, s5, 0
	global_load_dword v60, v6, s[0:1]
	global_load_dword v64, v36, s[12:13] offset:768
	global_load_dword v61, v7, s[0:1]
	global_load_dword v65, v34, s[12:13] offset:768
	global_load_dword v62, v8, s[0:1]
	global_load_dword v66, v32, s[12:13] offset:768
	global_load_dword v63, v9, s[0:1]
	global_load_dword v67, v30, s[12:13] offset:768
	s_add_u32 s0, s0, 0x40000
	s_addc_u32 s1, s1, 0
	s_waitcnt vmcnt(12)
	v_cvt_pk_bf16_f32 v52, v48, v49
	v_cvt_pk_bf16_f32 v53, v44, v45
	v_cvt_pk_bf16_f32 v54, v46, v47
	v_cvt_pk_bf16_f32 v55, v40, v41
	global_store_dword v6, v52, s[4:5]
	global_store_dword v7, v53, s[4:5]
	global_store_dword v8, v54, s[4:5]
	global_store_dword v9, v55, s[4:5]
	v_lshlrev_b32_e32 v56, 16, v68
	v_and_b32_e32 v57, 0xffff0000, v68
	v_lshlrev_b32_e32 v58, 16, v69
	v_and_b32_e32 v59, 0xffff0000, v69
	v_lshlrev_b32_e32 v110, 16, v70
	v_and_b32_e32 v111, 0xffff0000, v70
	v_lshlrev_b32_e32 v112, 16, v71
	v_and_b32_e32 v113, 0xffff0000, v71
	v_pk_fma_f32 v[48:49], v[48:49], v[72:73], v[56:57] op_sel_hi:[1,0,1]
	v_pk_fma_f32 v[44:45], v[44:45], v[72:73], v[58:59] op_sel:[0,1,0]
	v_pk_fma_f32 v[46:47], v[46:47], v[74:75], v[110:111] op_sel_hi:[1,0,1]
	v_pk_fma_f32 v[40:41], v[40:41], v[74:75], v[112:113] op_sel:[0,1,0]
	s_add_u32 s4, s4, 0x40000
	s_addc_u32 s5, s5, 0
	global_load_dword v68, v6, s[0:1]
	global_load_dword v72, v36, s[12:13] offset:832
	global_load_dword v69, v7, s[0:1]
	global_load_dword v73, v34, s[12:13] offset:832
	global_load_dword v70, v8, s[0:1]
	global_load_dword v74, v32, s[12:13] offset:832
	global_load_dword v71, v9, s[0:1]
	global_load_dword v75, v30, s[12:13] offset:832
	s_add_u32 s0, s0, 0x40000
	s_addc_u32 s1, s1, 0
	s_waitcnt vmcnt(12)
	v_cvt_pk_bf16_f32 v52, v48, v49
	v_cvt_pk_bf16_f32 v53, v44, v45
	v_cvt_pk_bf16_f32 v54, v46, v47
	v_cvt_pk_bf16_f32 v55, v40, v41
	global_store_dword v6, v52, s[4:5]
	global_store_dword v7, v53, s[4:5]
	global_store_dword v8, v54, s[4:5]
	global_store_dword v9, v55, s[4:5]
	v_lshlrev_b32_e32 v56, 16, v60
	v_and_b32_e32 v57, 0xffff0000, v60
	v_lshlrev_b32_e32 v58, 16, v61
	v_and_b32_e32 v59, 0xffff0000, v61
	v_lshlrev_b32_e32 v110, 16, v62
	v_and_b32_e32 v111, 0xffff0000, v62
	v_lshlrev_b32_e32 v112, 16, v63
	v_and_b32_e32 v113, 0xffff0000, v63
	v_pk_fma_f32 v[48:49], v[48:49], v[64:65], v[56:57] op_sel_hi:[1,0,1]
	v_pk_fma_f32 v[44:45], v[44:45], v[64:65], v[58:59] op_sel:[0,1,0]
	v_pk_fma_f32 v[46:47], v[46:47], v[66:67], v[110:111] op_sel_hi:[1,0,1]
	v_pk_fma_f32 v[40:41], v[40:41], v[66:67], v[112:113] op_sel:[0,1,0]
	s_add_u32 s4, s4, 0x40000
	s_addc_u32 s5, s5, 0
	global_load_dword v60, v6, s[0:1]
	global_load_dword v64, v36, s[12:13] offset:896
	global_load_dword v61, v7, s[0:1]
	global_load_dword v65, v34, s[12:13] offset:896
	global_load_dword v62, v8, s[0:1]
	global_load_dword v66, v32, s[12:13] offset:896
	global_load_dword v63, v9, s[0:1]
	global_load_dword v67, v30, s[12:13] offset:896
	s_add_u32 s0, s0, 0x40000
	s_addc_u32 s1, s1, 0
	s_waitcnt vmcnt(12)
	v_cvt_pk_bf16_f32 v52, v48, v49
	v_cvt_pk_bf16_f32 v53, v44, v45
	v_cvt_pk_bf16_f32 v54, v46, v47
	v_cvt_pk_bf16_f32 v55, v40, v41
	global_store_dword v6, v52, s[4:5]
	global_store_dword v7, v53, s[4:5]
	global_store_dword v8, v54, s[4:5]
	global_store_dword v9, v55, s[4:5]
	v_lshlrev_b32_e32 v56, 16, v68
	v_and_b32_e32 v57, 0xffff0000, v68
	v_lshlrev_b32_e32 v58, 16, v69
	v_and_b32_e32 v59, 0xffff0000, v69
	v_lshlrev_b32_e32 v110, 16, v70
	v_and_b32_e32 v111, 0xffff0000, v70
	v_lshlrev_b32_e32 v112, 16, v71
	v_and_b32_e32 v113, 0xffff0000, v71
	v_pk_fma_f32 v[48:49], v[48:49], v[72:73], v[56:57] op_sel_hi:[1,0,1]
	v_pk_fma_f32 v[44:45], v[44:45], v[72:73], v[58:59] op_sel:[0,1,0]
	v_pk_fma_f32 v[46:47], v[46:47], v[74:75], v[110:111] op_sel_hi:[1,0,1]
	v_pk_fma_f32 v[40:41], v[40:41], v[74:75], v[112:113] op_sel:[0,1,0]
	s_add_u32 s4, s4, 0x40000
	s_addc_u32 s5, s5, 0
	global_load_dword v68, v6, s[0:1]
	global_load_dword v72, v36, s[12:13] offset:960
	global_load_dword v69, v7, s[0:1]
	global_load_dword v73, v34, s[12:13] offset:960
	global_load_dword v70, v8, s[0:1]
	global_load_dword v74, v32, s[12:13] offset:960
	global_load_dword v71, v9, s[0:1]
	global_load_dword v75, v30, s[12:13] offset:960
	s_add_u32 s0, s0, 0x40000
	s_addc_u32 s1, s1, 0
	s_waitcnt vmcnt(12)
	v_cvt_pk_bf16_f32 v52, v48, v49
	v_cvt_pk_bf16_f32 v53, v44, v45
	v_cvt_pk_bf16_f32 v54, v46, v47
	v_cvt_pk_bf16_f32 v55, v40, v41
	global_store_dword v6, v52, s[4:5]
	global_store_dword v7, v53, s[4:5]
	global_store_dword v8, v54, s[4:5]
	global_store_dword v9, v55, s[4:5]
	v_lshlrev_b32_e32 v56, 16, v60
	v_and_b32_e32 v57, 0xffff0000, v60
	v_lshlrev_b32_e32 v58, 16, v61
	v_and_b32_e32 v59, 0xffff0000, v61
	v_lshlrev_b32_e32 v110, 16, v62
	v_and_b32_e32 v111, 0xffff0000, v62
	v_lshlrev_b32_e32 v112, 16, v63
	v_and_b32_e32 v113, 0xffff0000, v63
	v_pk_fma_f32 v[48:49], v[48:49], v[64:65], v[56:57] op_sel_hi:[1,0,1]
	v_pk_fma_f32 v[44:45], v[44:45], v[64:65], v[58:59] op_sel:[0,1,0]
	v_pk_fma_f32 v[46:47], v[46:47], v[66:67], v[110:111] op_sel_hi:[1,0,1]
	v_pk_fma_f32 v[40:41], v[40:41], v[66:67], v[112:113] op_sel:[0,1,0]
	s_add_u32 s4, s4, 0x40000
	s_addc_u32 s5, s5, 0
	global_load_dword v60, v6, s[0:1]
	global_load_dword v64, v36, s[12:13] offset:1024
	global_load_dword v61, v7, s[0:1]
	global_load_dword v65, v34, s[12:13] offset:1024
	global_load_dword v62, v8, s[0:1]
	global_load_dword v66, v32, s[12:13] offset:1024
	global_load_dword v63, v9, s[0:1]
	global_load_dword v67, v30, s[12:13] offset:1024
	s_add_u32 s0, s0, 0x40000
	s_addc_u32 s1, s1, 0
	s_waitcnt vmcnt(12)
	v_cvt_pk_bf16_f32 v52, v48, v49
	v_cvt_pk_bf16_f32 v53, v44, v45
	v_cvt_pk_bf16_f32 v54, v46, v47
	v_cvt_pk_bf16_f32 v55, v40, v41
	global_store_dword v6, v52, s[4:5]
	global_store_dword v7, v53, s[4:5]
	global_store_dword v8, v54, s[4:5]
	global_store_dword v9, v55, s[4:5]
	v_lshlrev_b32_e32 v56, 16, v68
	v_and_b32_e32 v57, 0xffff0000, v68
	v_lshlrev_b32_e32 v58, 16, v69
	v_and_b32_e32 v59, 0xffff0000, v69
	v_lshlrev_b32_e32 v110, 16, v70
	v_and_b32_e32 v111, 0xffff0000, v70
	v_lshlrev_b32_e32 v112, 16, v71
	v_and_b32_e32 v113, 0xffff0000, v71
	v_pk_fma_f32 v[48:49], v[48:49], v[72:73], v[56:57] op_sel_hi:[1,0,1]
	v_pk_fma_f32 v[44:45], v[44:45], v[72:73], v[58:59] op_sel:[0,1,0]
	v_pk_fma_f32 v[46:47], v[46:47], v[74:75], v[110:111] op_sel_hi:[1,0,1]
	v_pk_fma_f32 v[40:41], v[40:41], v[74:75], v[112:113] op_sel:[0,1,0]
	s_add_u32 s4, s4, 0x40000
	s_addc_u32 s5, s5, 0
	global_load_dword v68, v6, s[0:1]
	global_load_dword v72, v36, s[12:13] offset:1088
	global_load_dword v69, v7, s[0:1]
	global_load_dword v73, v34, s[12:13] offset:1088
	global_load_dword v70, v8, s[0:1]
	global_load_dword v74, v32, s[12:13] offset:1088
	global_load_dword v71, v9, s[0:1]
	global_load_dword v75, v30, s[12:13] offset:1088
	s_add_u32 s0, s0, 0x40000
	s_addc_u32 s1, s1, 0
	s_waitcnt vmcnt(12)
	v_cvt_pk_bf16_f32 v52, v48, v49
	v_cvt_pk_bf16_f32 v53, v44, v45
	v_cvt_pk_bf16_f32 v54, v46, v47
	v_cvt_pk_bf16_f32 v55, v40, v41
	global_store_dword v6, v52, s[4:5]
	global_store_dword v7, v53, s[4:5]
	global_store_dword v8, v54, s[4:5]
	global_store_dword v9, v55, s[4:5]
	v_lshlrev_b32_e32 v56, 16, v60
	v_and_b32_e32 v57, 0xffff0000, v60
	v_lshlrev_b32_e32 v58, 16, v61
	v_and_b32_e32 v59, 0xffff0000, v61
	v_lshlrev_b32_e32 v110, 16, v62
	v_and_b32_e32 v111, 0xffff0000, v62
	v_lshlrev_b32_e32 v112, 16, v63
	v_and_b32_e32 v113, 0xffff0000, v63
	v_pk_fma_f32 v[48:49], v[48:49], v[64:65], v[56:57] op_sel_hi:[1,0,1]
	v_pk_fma_f32 v[44:45], v[44:45], v[64:65], v[58:59] op_sel:[0,1,0]
	v_pk_fma_f32 v[46:47], v[46:47], v[66:67], v[110:111] op_sel_hi:[1,0,1]
	v_pk_fma_f32 v[40:41], v[40:41], v[66:67], v[112:113] op_sel:[0,1,0]
	s_add_u32 s4, s4, 0x40000
	s_addc_u32 s5, s5, 0
	global_load_dword v60, v6, s[0:1]
	global_load_dword v64, v36, s[12:13] offset:1152
	global_load_dword v61, v7, s[0:1]
	global_load_dword v65, v34, s[12:13] offset:1152
	global_load_dword v62, v8, s[0:1]
	global_load_dword v66, v32, s[12:13] offset:1152
	global_load_dword v63, v9, s[0:1]
	global_load_dword v67, v30, s[12:13] offset:1152
	s_add_u32 s0, s0, 0x40000
	s_addc_u32 s1, s1, 0
	s_waitcnt vmcnt(12)
	v_cvt_pk_bf16_f32 v52, v48, v49
	v_cvt_pk_bf16_f32 v53, v44, v45
	v_cvt_pk_bf16_f32 v54, v46, v47
	v_cvt_pk_bf16_f32 v55, v40, v41
	global_store_dword v6, v52, s[4:5]
	global_store_dword v7, v53, s[4:5]
	global_store_dword v8, v54, s[4:5]
	global_store_dword v9, v55, s[4:5]
	v_lshlrev_b32_e32 v56, 16, v68
	v_and_b32_e32 v57, 0xffff0000, v68
	v_lshlrev_b32_e32 v58, 16, v69
	v_and_b32_e32 v59, 0xffff0000, v69
	v_lshlrev_b32_e32 v110, 16, v70
	v_and_b32_e32 v111, 0xffff0000, v70
	v_lshlrev_b32_e32 v112, 16, v71
	v_and_b32_e32 v113, 0xffff0000, v71
	v_pk_fma_f32 v[48:49], v[48:49], v[72:73], v[56:57] op_sel_hi:[1,0,1]
	v_pk_fma_f32 v[44:45], v[44:45], v[72:73], v[58:59] op_sel:[0,1,0]
	v_pk_fma_f32 v[46:47], v[46:47], v[74:75], v[110:111] op_sel_hi:[1,0,1]
	v_pk_fma_f32 v[40:41], v[40:41], v[74:75], v[112:113] op_sel:[0,1,0]
	s_add_u32 s4, s4, 0x40000
	s_addc_u32 s5, s5, 0
	global_load_dword v68, v6, s[0:1]
	global_load_dword v72, v36, s[12:13] offset:1216
	global_load_dword v69, v7, s[0:1]
	global_load_dword v73, v34, s[12:13] offset:1216
	global_load_dword v70, v8, s[0:1]
	global_load_dword v74, v32, s[12:13] offset:1216
	global_load_dword v71, v9, s[0:1]
	global_load_dword v75, v30, s[12:13] offset:1216
	s_add_u32 s0, s0, 0x40000
	s_addc_u32 s1, s1, 0
	s_waitcnt vmcnt(12)
	v_cvt_pk_bf16_f32 v52, v48, v49
	v_cvt_pk_bf16_f32 v53, v44, v45
	v_cvt_pk_bf16_f32 v54, v46, v47
	v_cvt_pk_bf16_f32 v55, v40, v41
	global_store_dword v6, v52, s[4:5]
	global_store_dword v7, v53, s[4:5]
	global_store_dword v8, v54, s[4:5]
	global_store_dword v9, v55, s[4:5]
	v_lshlrev_b32_e32 v56, 16, v60
	v_and_b32_e32 v57, 0xffff0000, v60
	v_lshlrev_b32_e32 v58, 16, v61
	v_and_b32_e32 v59, 0xffff0000, v61
	v_lshlrev_b32_e32 v110, 16, v62
	v_and_b32_e32 v111, 0xffff0000, v62
	v_lshlrev_b32_e32 v112, 16, v63
	v_and_b32_e32 v113, 0xffff0000, v63
	v_pk_fma_f32 v[48:49], v[48:49], v[64:65], v[56:57] op_sel_hi:[1,0,1]
	v_pk_fma_f32 v[44:45], v[44:45], v[64:65], v[58:59] op_sel:[0,1,0]
	v_pk_fma_f32 v[46:47], v[46:47], v[66:67], v[110:111] op_sel_hi:[1,0,1]
	v_pk_fma_f32 v[40:41], v[40:41], v[66:67], v[112:113] op_sel:[0,1,0]
	s_add_u32 s4, s4, 0x40000
	s_addc_u32 s5, s5, 0
	global_load_dword v60, v6, s[0:1]
	global_load_dword v64, v36, s[12:13] offset:1280
	global_load_dword v61, v7, s[0:1]
	global_load_dword v65, v34, s[12:13] offset:1280
	global_load_dword v62, v8, s[0:1]
	global_load_dword v66, v32, s[12:13] offset:1280
	global_load_dword v63, v9, s[0:1]
	global_load_dword v67, v30, s[12:13] offset:1280
	s_add_u32 s0, s0, 0x40000
	s_addc_u32 s1, s1, 0
	s_waitcnt vmcnt(12)
	v_cvt_pk_bf16_f32 v52, v48, v49
	v_cvt_pk_bf16_f32 v53, v44, v45
	v_cvt_pk_bf16_f32 v54, v46, v47
	v_cvt_pk_bf16_f32 v55, v40, v41
	global_store_dword v6, v52, s[4:5]
	global_store_dword v7, v53, s[4:5]
	global_store_dword v8, v54, s[4:5]
	global_store_dword v9, v55, s[4:5]
	v_lshlrev_b32_e32 v56, 16, v68
	v_and_b32_e32 v57, 0xffff0000, v68
	v_lshlrev_b32_e32 v58, 16, v69
	v_and_b32_e32 v59, 0xffff0000, v69
	v_lshlrev_b32_e32 v110, 16, v70
	v_and_b32_e32 v111, 0xffff0000, v70
	v_lshlrev_b32_e32 v112, 16, v71
	v_and_b32_e32 v113, 0xffff0000, v71
	v_pk_fma_f32 v[48:49], v[48:49], v[72:73], v[56:57] op_sel_hi:[1,0,1]
	v_pk_fma_f32 v[44:45], v[44:45], v[72:73], v[58:59] op_sel:[0,1,0]
	v_pk_fma_f32 v[46:47], v[46:47], v[74:75], v[110:111] op_sel_hi:[1,0,1]
	v_pk_fma_f32 v[40:41], v[40:41], v[74:75], v[112:113] op_sel:[0,1,0]
	s_add_u32 s4, s4, 0x40000
	s_addc_u32 s5, s5, 0
	global_load_dword v68, v6, s[0:1]
	global_load_dword v72, v36, s[12:13] offset:1344
	global_load_dword v69, v7, s[0:1]
	global_load_dword v73, v34, s[12:13] offset:1344
	global_load_dword v70, v8, s[0:1]
	global_load_dword v74, v32, s[12:13] offset:1344
	global_load_dword v71, v9, s[0:1]
	global_load_dword v75, v30, s[12:13] offset:1344
	s_add_u32 s0, s0, 0x40000
	s_addc_u32 s1, s1, 0
	s_waitcnt vmcnt(12)
	v_cvt_pk_bf16_f32 v52, v48, v49
	v_cvt_pk_bf16_f32 v53, v44, v45
	v_cvt_pk_bf16_f32 v54, v46, v47
	v_cvt_pk_bf16_f32 v55, v40, v41
	global_store_dword v6, v52, s[4:5]
	global_store_dword v7, v53, s[4:5]
	global_store_dword v8, v54, s[4:5]
	global_store_dword v9, v55, s[4:5]
	v_lshlrev_b32_e32 v56, 16, v60
	v_and_b32_e32 v57, 0xffff0000, v60
	v_lshlrev_b32_e32 v58, 16, v61
	v_and_b32_e32 v59, 0xffff0000, v61
	v_lshlrev_b32_e32 v110, 16, v62
	v_and_b32_e32 v111, 0xffff0000, v62
	v_lshlrev_b32_e32 v112, 16, v63
	v_and_b32_e32 v113, 0xffff0000, v63
	v_pk_fma_f32 v[48:49], v[48:49], v[64:65], v[56:57] op_sel_hi:[1,0,1]
	v_pk_fma_f32 v[44:45], v[44:45], v[64:65], v[58:59] op_sel:[0,1,0]
	v_pk_fma_f32 v[46:47], v[46:47], v[66:67], v[110:111] op_sel_hi:[1,0,1]
	v_pk_fma_f32 v[40:41], v[40:41], v[66:67], v[112:113] op_sel:[0,1,0]
	s_add_u32 s4, s4, 0x40000
	s_addc_u32 s5, s5, 0
	global_load_dword v60, v6, s[0:1]
	global_load_dword v64, v36, s[12:13] offset:1408
	global_load_dword v61, v7, s[0:1]
	global_load_dword v65, v34, s[12:13] offset:1408
	global_load_dword v62, v8, s[0:1]
	global_load_dword v66, v32, s[12:13] offset:1408
	global_load_dword v63, v9, s[0:1]
	global_load_dword v67, v30, s[12:13] offset:1408
	s_add_u32 s0, s0, 0x40000
	s_addc_u32 s1, s1, 0
	s_waitcnt vmcnt(12)
	v_cvt_pk_bf16_f32 v52, v48, v49
	v_cvt_pk_bf16_f32 v53, v44, v45
	v_cvt_pk_bf16_f32 v54, v46, v47
	v_cvt_pk_bf16_f32 v55, v40, v41
	global_store_dword v6, v52, s[4:5]
	global_store_dword v7, v53, s[4:5]
	global_store_dword v8, v54, s[4:5]
	global_store_dword v9, v55, s[4:5]
	v_lshlrev_b32_e32 v56, 16, v68
	v_and_b32_e32 v57, 0xffff0000, v68
	v_lshlrev_b32_e32 v58, 16, v69
	v_and_b32_e32 v59, 0xffff0000, v69
	v_lshlrev_b32_e32 v110, 16, v70
	v_and_b32_e32 v111, 0xffff0000, v70
	v_lshlrev_b32_e32 v112, 16, v71
	v_and_b32_e32 v113, 0xffff0000, v71
	v_pk_fma_f32 v[48:49], v[48:49], v[72:73], v[56:57] op_sel_hi:[1,0,1]
	v_pk_fma_f32 v[44:45], v[44:45], v[72:73], v[58:59] op_sel:[0,1,0]
	v_pk_fma_f32 v[46:47], v[46:47], v[74:75], v[110:111] op_sel_hi:[1,0,1]
	v_pk_fma_f32 v[40:41], v[40:41], v[74:75], v[112:113] op_sel:[0,1,0]
	s_add_u32 s4, s4, 0x40000
	s_addc_u32 s5, s5, 0
	global_load_dword v68, v6, s[0:1]
	global_load_dword v72, v36, s[12:13] offset:1472
	global_load_dword v69, v7, s[0:1]
	global_load_dword v73, v34, s[12:13] offset:1472
	global_load_dword v70, v8, s[0:1]
	global_load_dword v74, v32, s[12:13] offset:1472
	global_load_dword v71, v9, s[0:1]
	global_load_dword v75, v30, s[12:13] offset:1472
	s_add_u32 s0, s0, 0x40000
	s_addc_u32 s1, s1, 0
	s_waitcnt vmcnt(12)
	v_cvt_pk_bf16_f32 v52, v48, v49
	v_cvt_pk_bf16_f32 v53, v44, v45
	v_cvt_pk_bf16_f32 v54, v46, v47
	v_cvt_pk_bf16_f32 v55, v40, v41
	global_store_dword v6, v52, s[4:5]
	global_store_dword v7, v53, s[4:5]
	global_store_dword v8, v54, s[4:5]
	global_store_dword v9, v55, s[4:5]
	v_lshlrev_b32_e32 v56, 16, v60
	v_and_b32_e32 v57, 0xffff0000, v60
	v_lshlrev_b32_e32 v58, 16, v61
	v_and_b32_e32 v59, 0xffff0000, v61
	v_lshlrev_b32_e32 v110, 16, v62
	v_and_b32_e32 v111, 0xffff0000, v62
	v_lshlrev_b32_e32 v112, 16, v63
	v_and_b32_e32 v113, 0xffff0000, v63
	v_pk_fma_f32 v[48:49], v[48:49], v[64:65], v[56:57] op_sel_hi:[1,0,1]
	v_pk_fma_f32 v[44:45], v[44:45], v[64:65], v[58:59] op_sel:[0,1,0]
	v_pk_fma_f32 v[46:47], v[46:47], v[66:67], v[110:111] op_sel_hi:[1,0,1]
	v_pk_fma_f32 v[40:41], v[40:41], v[66:67], v[112:113] op_sel:[0,1,0]
	s_add_u32 s4, s4, 0x40000
	s_addc_u32 s5, s5, 0
	global_load_dword v60, v6, s[0:1]
	global_load_dword v64, v36, s[12:13] offset:1536
	global_load_dword v61, v7, s[0:1]
	global_load_dword v65, v34, s[12:13] offset:1536
	global_load_dword v62, v8, s[0:1]
	global_load_dword v66, v32, s[12:13] offset:1536
	global_load_dword v63, v9, s[0:1]
	global_load_dword v67, v30, s[12:13] offset:1536
	s_add_u32 s0, s0, 0x40000
	s_addc_u32 s1, s1, 0
	s_waitcnt vmcnt(12)
	v_cvt_pk_bf16_f32 v52, v48, v49
	v_cvt_pk_bf16_f32 v53, v44, v45
	v_cvt_pk_bf16_f32 v54, v46, v47
	v_cvt_pk_bf16_f32 v55, v40, v41
	global_store_dword v6, v52, s[4:5]
	global_store_dword v7, v53, s[4:5]
	global_store_dword v8, v54, s[4:5]
	global_store_dword v9, v55, s[4:5]
	v_lshlrev_b32_e32 v56, 16, v68
	v_and_b32_e32 v57, 0xffff0000, v68
	v_lshlrev_b32_e32 v58, 16, v69
	v_and_b32_e32 v59, 0xffff0000, v69
	v_lshlrev_b32_e32 v110, 16, v70
	v_and_b32_e32 v111, 0xffff0000, v70
	v_lshlrev_b32_e32 v112, 16, v71
	v_and_b32_e32 v113, 0xffff0000, v71
	v_pk_fma_f32 v[48:49], v[48:49], v[72:73], v[56:57] op_sel_hi:[1,0,1]
	v_pk_fma_f32 v[44:45], v[44:45], v[72:73], v[58:59] op_sel:[0,1,0]
	v_pk_fma_f32 v[46:47], v[46:47], v[74:75], v[110:111] op_sel_hi:[1,0,1]
	v_pk_fma_f32 v[40:41], v[40:41], v[74:75], v[112:113] op_sel:[0,1,0]
	s_add_u32 s4, s4, 0x40000
	s_addc_u32 s5, s5, 0
	global_load_dword v68, v6, s[0:1]
	global_load_dword v72, v36, s[12:13] offset:1600
	global_load_dword v69, v7, s[0:1]
	global_load_dword v73, v34, s[12:13] offset:1600
	global_load_dword v70, v8, s[0:1]
	global_load_dword v74, v32, s[12:13] offset:1600
	global_load_dword v71, v9, s[0:1]
	global_load_dword v75, v30, s[12:13] offset:1600
	s_add_u32 s0, s0, 0x40000
	s_addc_u32 s1, s1, 0
	s_waitcnt vmcnt(12)
	v_cvt_pk_bf16_f32 v52, v48, v49
	v_cvt_pk_bf16_f32 v53, v44, v45
	v_cvt_pk_bf16_f32 v54, v46, v47
	v_cvt_pk_bf16_f32 v55, v40, v41
	global_store_dword v6, v52, s[4:5]
	global_store_dword v7, v53, s[4:5]
	global_store_dword v8, v54, s[4:5]
	global_store_dword v9, v55, s[4:5]
	v_lshlrev_b32_e32 v56, 16, v60
	v_and_b32_e32 v57, 0xffff0000, v60
	v_lshlrev_b32_e32 v58, 16, v61
	v_and_b32_e32 v59, 0xffff0000, v61
	v_lshlrev_b32_e32 v110, 16, v62
	v_and_b32_e32 v111, 0xffff0000, v62
	v_lshlrev_b32_e32 v112, 16, v63
	v_and_b32_e32 v113, 0xffff0000, v63
	v_pk_fma_f32 v[48:49], v[48:49], v[64:65], v[56:57] op_sel_hi:[1,0,1]
	v_pk_fma_f32 v[44:45], v[44:45], v[64:65], v[58:59] op_sel:[0,1,0]
	v_pk_fma_f32 v[46:47], v[46:47], v[66:67], v[110:111] op_sel_hi:[1,0,1]
	v_pk_fma_f32 v[40:41], v[40:41], v[66:67], v[112:113] op_sel:[0,1,0]
	s_add_u32 s4, s4, 0x40000
	s_addc_u32 s5, s5, 0
	global_load_dword v60, v6, s[0:1]
	global_load_dword v64, v36, s[12:13] offset:1664
	global_load_dword v61, v7, s[0:1]
	global_load_dword v65, v34, s[12:13] offset:1664
	global_load_dword v62, v8, s[0:1]
	global_load_dword v66, v32, s[12:13] offset:1664
	global_load_dword v63, v9, s[0:1]
	global_load_dword v67, v30, s[12:13] offset:1664
	s_add_u32 s0, s0, 0x40000
	s_addc_u32 s1, s1, 0
	s_waitcnt vmcnt(12)
	v_cvt_pk_bf16_f32 v52, v48, v49
	v_cvt_pk_bf16_f32 v53, v44, v45
	v_cvt_pk_bf16_f32 v54, v46, v47
	v_cvt_pk_bf16_f32 v55, v40, v41
	global_store_dword v6, v52, s[4:5]
	global_store_dword v7, v53, s[4:5]
	global_store_dword v8, v54, s[4:5]
	global_store_dword v9, v55, s[4:5]
	v_lshlrev_b32_e32 v56, 16, v68
	v_and_b32_e32 v57, 0xffff0000, v68
	v_lshlrev_b32_e32 v58, 16, v69
	v_and_b32_e32 v59, 0xffff0000, v69
	v_lshlrev_b32_e32 v110, 16, v70
	v_and_b32_e32 v111, 0xffff0000, v70
	v_lshlrev_b32_e32 v112, 16, v71
	v_and_b32_e32 v113, 0xffff0000, v71
	v_pk_fma_f32 v[48:49], v[48:49], v[72:73], v[56:57] op_sel_hi:[1,0,1]
	v_pk_fma_f32 v[44:45], v[44:45], v[72:73], v[58:59] op_sel:[0,1,0]
	v_pk_fma_f32 v[46:47], v[46:47], v[74:75], v[110:111] op_sel_hi:[1,0,1]
	v_pk_fma_f32 v[40:41], v[40:41], v[74:75], v[112:113] op_sel:[0,1,0]
	s_add_u32 s4, s4, 0x40000
	s_addc_u32 s5, s5, 0
	global_load_dword v68, v6, s[0:1]
	global_load_dword v72, v36, s[12:13] offset:1728
	global_load_dword v69, v7, s[0:1]
	global_load_dword v73, v34, s[12:13] offset:1728
	global_load_dword v70, v8, s[0:1]
	global_load_dword v74, v32, s[12:13] offset:1728
	global_load_dword v71, v9, s[0:1]
	global_load_dword v75, v30, s[12:13] offset:1728
	s_add_u32 s0, s0, 0x40000
	s_addc_u32 s1, s1, 0
	s_waitcnt vmcnt(12)
	v_cvt_pk_bf16_f32 v52, v48, v49
	v_cvt_pk_bf16_f32 v53, v44, v45
	v_cvt_pk_bf16_f32 v54, v46, v47
	v_cvt_pk_bf16_f32 v55, v40, v41
	global_store_dword v6, v52, s[4:5]
	global_store_dword v7, v53, s[4:5]
	global_store_dword v8, v54, s[4:5]
	global_store_dword v9, v55, s[4:5]
	v_lshlrev_b32_e32 v56, 16, v60
	v_and_b32_e32 v57, 0xffff0000, v60
	v_lshlrev_b32_e32 v58, 16, v61
	v_and_b32_e32 v59, 0xffff0000, v61
	v_lshlrev_b32_e32 v110, 16, v62
	v_and_b32_e32 v111, 0xffff0000, v62
	v_lshlrev_b32_e32 v112, 16, v63
	v_and_b32_e32 v113, 0xffff0000, v63
	v_pk_fma_f32 v[48:49], v[48:49], v[64:65], v[56:57] op_sel_hi:[1,0,1]
	v_pk_fma_f32 v[44:45], v[44:45], v[64:65], v[58:59] op_sel:[0,1,0]
	v_pk_fma_f32 v[46:47], v[46:47], v[66:67], v[110:111] op_sel_hi:[1,0,1]
	v_pk_fma_f32 v[40:41], v[40:41], v[66:67], v[112:113] op_sel:[0,1,0]
	s_add_u32 s4, s4, 0x40000
	s_addc_u32 s5, s5, 0
	global_load_dword v60, v6, s[0:1]
	global_load_dword v64, v36, s[12:13] offset:1792
	global_load_dword v61, v7, s[0:1]
	global_load_dword v65, v34, s[12:13] offset:1792
	global_load_dword v62, v8, s[0:1]
	global_load_dword v66, v32, s[12:13] offset:1792
	global_load_dword v63, v9, s[0:1]
	global_load_dword v67, v30, s[12:13] offset:1792
	s_add_u32 s0, s0, 0x40000
	s_addc_u32 s1, s1, 0
	s_waitcnt vmcnt(12)
	v_cvt_pk_bf16_f32 v52, v48, v49
	v_cvt_pk_bf16_f32 v53, v44, v45
	v_cvt_pk_bf16_f32 v54, v46, v47
	v_cvt_pk_bf16_f32 v55, v40, v41
	global_store_dword v6, v52, s[4:5]
	global_store_dword v7, v53, s[4:5]
	global_store_dword v8, v54, s[4:5]
	global_store_dword v9, v55, s[4:5]
	v_lshlrev_b32_e32 v56, 16, v68
	v_and_b32_e32 v57, 0xffff0000, v68
	v_lshlrev_b32_e32 v58, 16, v69
	v_and_b32_e32 v59, 0xffff0000, v69
	v_lshlrev_b32_e32 v110, 16, v70
	v_and_b32_e32 v111, 0xffff0000, v70
	v_lshlrev_b32_e32 v112, 16, v71
	v_and_b32_e32 v113, 0xffff0000, v71
	v_pk_fma_f32 v[48:49], v[48:49], v[72:73], v[56:57] op_sel_hi:[1,0,1]
	v_pk_fma_f32 v[44:45], v[44:45], v[72:73], v[58:59] op_sel:[0,1,0]
	v_pk_fma_f32 v[46:47], v[46:47], v[74:75], v[110:111] op_sel_hi:[1,0,1]
	v_pk_fma_f32 v[40:41], v[40:41], v[74:75], v[112:113] op_sel:[0,1,0]
	s_add_u32 s4, s4, 0x40000
	s_addc_u32 s5, s5, 0
	global_load_dword v68, v6, s[0:1]
	global_load_dword v72, v36, s[12:13] offset:1856
	global_load_dword v69, v7, s[0:1]
	global_load_dword v73, v34, s[12:13] offset:1856
	global_load_dword v70, v8, s[0:1]
	global_load_dword v74, v32, s[12:13] offset:1856
	global_load_dword v71, v9, s[0:1]
	global_load_dword v75, v30, s[12:13] offset:1856
	s_add_u32 s0, s0, 0x40000
	s_addc_u32 s1, s1, 0
	s_waitcnt vmcnt(12)
	v_cvt_pk_bf16_f32 v52, v48, v49
	v_cvt_pk_bf16_f32 v53, v44, v45
	v_cvt_pk_bf16_f32 v54, v46, v47
	v_cvt_pk_bf16_f32 v55, v40, v41
	global_store_dword v6, v52, s[4:5]
	global_store_dword v7, v53, s[4:5]
	global_store_dword v8, v54, s[4:5]
	global_store_dword v9, v55, s[4:5]
	v_lshlrev_b32_e32 v56, 16, v60
	v_and_b32_e32 v57, 0xffff0000, v60
	v_lshlrev_b32_e32 v58, 16, v61
	v_and_b32_e32 v59, 0xffff0000, v61
	v_lshlrev_b32_e32 v110, 16, v62
	v_and_b32_e32 v111, 0xffff0000, v62
	v_lshlrev_b32_e32 v112, 16, v63
	v_and_b32_e32 v113, 0xffff0000, v63
	v_pk_fma_f32 v[48:49], v[48:49], v[64:65], v[56:57] op_sel_hi:[1,0,1]
	v_pk_fma_f32 v[44:45], v[44:45], v[64:65], v[58:59] op_sel:[0,1,0]
	v_pk_fma_f32 v[46:47], v[46:47], v[66:67], v[110:111] op_sel_hi:[1,0,1]
	v_pk_fma_f32 v[40:41], v[40:41], v[66:67], v[112:113] op_sel:[0,1,0]
	s_add_u32 s4, s4, 0x40000
	s_addc_u32 s5, s5, 0
	global_load_dword v60, v6, s[0:1]
	global_load_dword v64, v36, s[12:13] offset:1920
	global_load_dword v61, v7, s[0:1]
	global_load_dword v65, v34, s[12:13] offset:1920
	global_load_dword v62, v8, s[0:1]
	global_load_dword v66, v32, s[12:13] offset:1920
	global_load_dword v63, v9, s[0:1]
	global_load_dword v67, v30, s[12:13] offset:1920
	s_add_u32 s0, s0, 0x40000
	s_addc_u32 s1, s1, 0
	s_waitcnt vmcnt(12)
	v_cvt_pk_bf16_f32 v52, v48, v49
	v_cvt_pk_bf16_f32 v53, v44, v45
	v_cvt_pk_bf16_f32 v54, v46, v47
	v_cvt_pk_bf16_f32 v55, v40, v41
	global_store_dword v6, v52, s[4:5]
	global_store_dword v7, v53, s[4:5]
	global_store_dword v8, v54, s[4:5]
	global_store_dword v9, v55, s[4:5]
	v_lshlrev_b32_e32 v56, 16, v68
	v_and_b32_e32 v57, 0xffff0000, v68
	v_lshlrev_b32_e32 v58, 16, v69
	v_and_b32_e32 v59, 0xffff0000, v69
	v_lshlrev_b32_e32 v110, 16, v70
	v_and_b32_e32 v111, 0xffff0000, v70
	v_lshlrev_b32_e32 v112, 16, v71
	v_and_b32_e32 v113, 0xffff0000, v71
	v_pk_fma_f32 v[48:49], v[48:49], v[72:73], v[56:57] op_sel_hi:[1,0,1]
	v_pk_fma_f32 v[44:45], v[44:45], v[72:73], v[58:59] op_sel:[0,1,0]
	v_pk_fma_f32 v[46:47], v[46:47], v[74:75], v[110:111] op_sel_hi:[1,0,1]
	v_pk_fma_f32 v[40:41], v[40:41], v[74:75], v[112:113] op_sel:[0,1,0]
	s_add_u32 s4, s4, 0x40000
	s_addc_u32 s5, s5, 0
	global_load_dword v68, v6, s[0:1]
	global_load_dword v72, v36, s[12:13] offset:1984
	global_load_dword v69, v7, s[0:1]
	global_load_dword v73, v34, s[12:13] offset:1984
	global_load_dword v70, v8, s[0:1]
	global_load_dword v74, v32, s[12:13] offset:1984
	global_load_dword v71, v9, s[0:1]
	global_load_dword v75, v30, s[12:13] offset:1984
	s_add_u32 s0, s0, 0x40000
	s_addc_u32 s1, s1, 0
	s_waitcnt vmcnt(12)
	v_cvt_pk_bf16_f32 v52, v48, v49
	v_cvt_pk_bf16_f32 v53, v44, v45
	v_cvt_pk_bf16_f32 v54, v46, v47
	v_cvt_pk_bf16_f32 v55, v40, v41
	global_store_dword v6, v52, s[4:5]
	global_store_dword v7, v53, s[4:5]
	global_store_dword v8, v54, s[4:5]
	global_store_dword v9, v55, s[4:5]
	v_lshlrev_b32_e32 v56, 16, v60
	v_and_b32_e32 v57, 0xffff0000, v60
	v_lshlrev_b32_e32 v58, 16, v61
	v_and_b32_e32 v59, 0xffff0000, v61
	v_lshlrev_b32_e32 v110, 16, v62
	v_and_b32_e32 v111, 0xffff0000, v62
	v_lshlrev_b32_e32 v112, 16, v63
	v_and_b32_e32 v113, 0xffff0000, v63
	v_pk_fma_f32 v[48:49], v[48:49], v[64:65], v[56:57] op_sel_hi:[1,0,1]
	v_pk_fma_f32 v[44:45], v[44:45], v[64:65], v[58:59] op_sel:[0,1,0]
	v_pk_fma_f32 v[46:47], v[46:47], v[66:67], v[110:111] op_sel_hi:[1,0,1]
	v_pk_fma_f32 v[40:41], v[40:41], v[66:67], v[112:113] op_sel:[0,1,0]
	s_add_u32 s4, s4, 0x40000
	s_addc_u32 s5, s5, 0
	s_waitcnt vmcnt(4)
	v_cvt_pk_bf16_f32 v52, v48, v49
	v_cvt_pk_bf16_f32 v53, v44, v45
	v_cvt_pk_bf16_f32 v54, v46, v47
	v_cvt_pk_bf16_f32 v55, v40, v41
	global_store_dword v6, v52, s[4:5]
	global_store_dword v7, v53, s[4:5]
	global_store_dword v8, v54, s[4:5]
	global_store_dword v9, v55, s[4:5]
	v_lshlrev_b32_e32 v56, 16, v68
	v_and_b32_e32 v57, 0xffff0000, v68
	v_lshlrev_b32_e32 v58, 16, v69
	v_and_b32_e32 v59, 0xffff0000, v69
	v_lshlrev_b32_e32 v110, 16, v70
	v_and_b32_e32 v111, 0xffff0000, v70
	v_lshlrev_b32_e32 v112, 16, v71
	v_and_b32_e32 v113, 0xffff0000, v71
	v_pk_fma_f32 v[48:49], v[48:49], v[72:73], v[56:57] op_sel_hi:[1,0,1]
	v_pk_fma_f32 v[44:45], v[44:45], v[72:73], v[58:59] op_sel:[0,1,0]
	v_pk_fma_f32 v[46:47], v[46:47], v[74:75], v[110:111] op_sel_hi:[1,0,1]
	v_pk_fma_f32 v[40:41], v[40:41], v[74:75], v[112:113] op_sel:[0,1,0]
	s_add_u32 s4, s4, 0x40000
	s_addc_u32 s5, s5, 0
	s_branch .LBB0_574
